# speedup vs baseline: 1.0506x; 1.0001x over previous
; __device__ __forceinline__ void attn_item(const int WV, const Params& P, int bh, int qb) {
;     ...
;       float mx = -INFINITY;
; #pragma unroll
;       for (int kb = 0; kb < 2; ++kb)
; #pragma unroll
;         for (int i = 0; i < 16; ++i) mx = fmaxf(mx, st[kb][i]);
;       {
;         auto rr = __builtin_amdgcn_permlane32_swap(__float_as_uint(mx), __float_as_uint(mx), false, false);
;         mx = fmaxf(__uint_as_float(rr[0]), __uint_as_float(rr[1]));
;       }
.LBB0_389:
	s_or_b64 exec, exec, s[20:21]
	v_add3_u32 v232, s34, v134, v128
	v_lshrrev_b32_e32 v233, 2, v162
	v_and_b32_e32 v233, 8, v233
	v_add_u32_e32 v232, v232, v233
	v_add_u32_e32 v233, 0x2000, v232
	v_add_u32_e32 v234, 0x3000, v232
	ds_read_b128 v[200:203], v233 offset:1024
	ds_read_b128 v[204:207], v234 offset:1536
	ds_read_b128 v[208:211], v233 offset:1056
	ds_read_b128 v[212:215], v234 offset:1568
	ds_read_b128 v[216:219], v233 offset:1088
	ds_read_b128 v[220:223], v234 offset:1600
	ds_read_b128 v[224:227], v233 offset:1120
	ds_read_b128 v[228:231], v234 offset:1632
	v_max3_f32 v0, v64, s76, v65
	v_max3_f32 v2, v48, s76, v49
	v_max3_f32 v0, v0, v66, v67
	v_max3_f32 v2, v2, v50, v51
	v_max3_f32 v0, v0, v68, v69
	v_max3_f32 v2, v2, v52, v53
	v_max3_f32 v0, v0, v70, v71
	v_max3_f32 v2, v2, v54, v55
	v_max3_f32 v0, v0, v72, v73
	v_max3_f32 v2, v2, v56, v57
	v_max3_f32 v0, v0, v74, v75
	v_max3_f32 v2, v2, v58, v59
	v_max3_f32 v0, v0, v76, v77
	v_max3_f32 v2, v2, v60, v61
	v_max3_f32 v0, v0, v78, v79
	v_max3_f32 v2, v2, v62, v63
	v_max_f32_e32 v0, v0, v2
	v_mov_b32_e32 v2, v0
	s_nop 1
	v_permlane32_swap_b32_e32 v0, v2
	v_max_f32_e32 v0, v0, v2
	v_sub_f32_e32 v2, v0, v137
	v_cmp_lt_f32_e32 vcc, 0x41c00000, v2
	s_cbranch_vccz .Lat_noresc_a
	v_max_f32_e32 v138, v137, v0
	v_sub_f32_e32 v2, v137, v138
	v_exp_f32_e32 v2, v2
	v_mov_b32_e32 v137, v138
	s_nop 0
	v_mul_f32_e32 v136, v136, v2
	v_mul_f32_e32 v32, v32, v2
	v_mul_f32_e32 v33, v33, v2
	v_mul_f32_e32 v34, v34, v2
	v_mul_f32_e32 v35, v35, v2
	v_mul_f32_e32 v36, v36, v2
	v_mul_f32_e32 v37, v37, v2
	v_mul_f32_e32 v38, v38, v2
	v_mul_f32_e32 v39, v39, v2
	v_mul_f32_e32 v40, v40, v2
	v_mul_f32_e32 v41, v41, v2
	v_mul_f32_e32 v42, v42, v2
	v_mul_f32_e32 v43, v43, v2
	v_mul_f32_e32 v44, v44, v2
	v_mul_f32_e32 v45, v45, v2
	v_mul_f32_e32 v46, v46, v2
	v_mul_f32_e32 v47, v47, v2
	v_mul_f32_e32 v16, v16, v2
	v_mul_f32_e32 v17, v17, v2
	v_mul_f32_e32 v18, v18, v2
	v_mul_f32_e32 v19, v19, v2
	v_mul_f32_e32 v20, v20, v2
	v_mul_f32_e32 v21, v21, v2
	v_mul_f32_e32 v22, v22, v2
	v_mul_f32_e32 v23, v23, v2
	v_mul_f32_e32 v24, v24, v2
	v_mul_f32_e32 v25, v25, v2
	v_mul_f32_e32 v26, v26, v2
	v_mul_f32_e32 v27, v27, v2
	v_mul_f32_e32 v28, v28, v2
	v_mul_f32_e32 v29, v29, v2
	v_mul_f32_e32 v30, v30, v2
	v_mul_f32_e32 v31, v31, v2
